# GEMM1 per-XCD tile rotation in multiples of 4 tiles (slot-aligned: each 32-CU slot keeps a homogeneous tile type)
# baseline (speedup 1.0000x reference)
;     __host__ __device__ bool next(int i, Unit& u) const {
;         const long L = (long)i * G + c; if (L >= nwg) return false;
;         int wgid = (int)L; { const int q = nwg / NXCD, r = nwg % NXCD, xcd = wgid % NXCD, off = wgid / NXCD; wgid = (xcd < r ? xcd * (q + 1) : r * (q + 1) + (xcd - r) * q) + off; }
;         const int nig = WGM * nN, gid = wgid / nig, fm = gid * WGM, gsz = (nM - fm) < WGM ? (nM - fm) : WGM;
;         u.pm = fm + ((wgid % nig) % gsz); u.pn = (wgid % nig) / gsz; return true;
;     }
.LBB0_339:
	s_cmp_lt_i32 s92, 3
	s_cselect_b64 s[2:3], -1, 0
	s_and_b64 s[0:1], s[2:3], s[0:1]
	s_andn2_b64 vcc, exec, s[0:1]
	s_mov_b64 s[0:1], s[48:49]
	s_mov_b64 s[14:15], s[62:63]
	v_writelane_b32 v254, s0, 23
	s_nop 1
	v_writelane_b32 v254, s1, 24
	v_writelane_b32 v254, s2, 25
	v_writelane_b32 v254, s3, 26
	v_writelane_b32 v254, s4, 27
	v_writelane_b32 v254, s5, 28
	v_writelane_b32 v254, s6, 29
	v_writelane_b32 v254, s7, 30
	v_writelane_b32 v254, s8, 31
	v_writelane_b32 v254, s9, 32
	v_writelane_b32 v254, s10, 33
	v_writelane_b32 v254, s11, 34
	v_writelane_b32 v254, s12, 35
	v_writelane_b32 v254, s13, 36
	v_writelane_b32 v254, s14, 37
	v_writelane_b32 v254, s15, 38
	s_cbranch_vccnz .LBB0_1057
	s_cmpk_lt_i32 s80, 0xb80
	v_readfirstlane_b32 s11, v200
	s_movk_i32 s0, 0x400
	s_cselect_b64 s[2:3], -1, 0
	s_cmpk_gt_i32 s80, 0xb7f
	s_cbranch_scc1 .LBB0_342
	s_ashr_i32 s1, s80, 31
	s_lshr_b32 s1, s1, 29
	s_add_i32 s1, s80, s1
	s_ashr_i32 s4, s1, 3
	s_and_b32 s1, s1, -8
	s_sub_i32 s1, s80, s1
	s_cmp_lt_i32 s1, 0
	s_movk_i32 s5, 0x171
	s_cselect_b32 s5, s5, 0x170
	s_mul_i32 s1, s1, s5
	s_add_i32 s1, s1, s4
	s_mul_hi_i32 s4, s1, 0xb21642c9
	s_add_i32 s4, s4, s1
	s_lshr_b32 s5, s4, 31
	s_ashr_i32 s4, s4, 7
	s_add_i32 s4, s4, s5
	s_lshl_b32 s5, s4, 3
	s_mulk_i32 s4, 0xb8
	s_sub_i32 s1, s1, s4
	s_sext_i32_i16 s4, s1
	s_bfe_u32 s4, s4, 0x3001c
	s_add_i32 s4, s1, s4
	s_sext_i32_i16 s6, s4
	s_and_b32 s4, s4, 0xfff8
	s_sub_i32 s1, s1, s4
	s_sext_i32_i16 s1, s1
	s_add_i32 s33, s5, s1
	s_ashr_i32 s10, s6, 3
	s_and_b32 s32, s80, 7
	s_sub_i32 s1, s32, 6
	s_cmp_ge_i32 s32, 6
	s_cselect_b32 s32, s1, s32
	s_lshl_b32 s32, s32, 2
	s_add_i32 s10, s10, s32
	s_sub_i32 s1, s10, 23
	s_cmp_ge_i32 s10, 23
	s_cselect_b32 s10, s1, s10
